# attention loop-edge edit: back edge rotated so the loop-back barrier is the loop head; exit path has its own barrier copy; l combine moved before it
# speedup vs baseline: 1.0023x; 1.0023x over previous
; #define SWAIT() do { if constexpr (SDEPTH == 2) asm volatile("s_waitcnt vmcnt(4)" ::: "memory"); else asm volatile("s_waitcnt vmcnt(0)" ::: "memory"); } while (0)
; #define RESC(a) do { if (__any((a) < 1.f)) { if (hi == 0) al_l[r32] = (a); asm volatile("s_waitcnt lgkmcnt(0)" ::: "memory"); \
;     for (int d = 0; d < 4; ++d) for (int r = 0; r < 16; ++r) o[d][r] *= al_l[crow(r, hi)]; } } while (0)
; template <typename TQ>
; __device__ __forceinline__ void attn_dense_body(const TQ* __restrict__ Qb, const bf16* __restrict__ Kh, const bf16* __restrict__ Vh,
;                                                 unsigned short* __restrict__ Ob, int seq, char* lds, const int wave_s) {
;     ...
;     __syncthreads(); SWAIT(); SWRITE(1, SO);
;     RESC(alA); __syncthreads();
.Lattn_head:
	s_barrier

; #define SWAIT() do { if constexpr (SDEPTH == 2) asm volatile("s_waitcnt vmcnt(4)" ::: "memory"); else asm volatile("s_waitcnt vmcnt(0)" ::: "memory"); } while (0)
; #define RESC(a) do { if (__any((a) < 1.f)) { if (hi == 0) al_l[r32] = (a); asm volatile("s_waitcnt lgkmcnt(0)" ::: "memory"); \
;     for (int d = 0; d < 4; ++d) for (int r = 0; r < 16; ++r) o[d][r] *= al_l[crow(r, hi)]; } } while (0)
; __device__ __forceinline__ void partialSM(f32x16& p0, f32x16& p1, float& m_reg, float& mn, float& alpha) {
;     ...
;   float mnC = -mn * C;
;   for (int r = 0; r < 16; ++r) p0[r] = fmaf(p0[r], C, mnC); for (int r = 0; r < 16; ++r) p1[r] = fmaf(p1[r], C, mnC);
;   for (int r = 0; r < 16; ++r) p0[r] = __builtin_amdgcn_exp2f(p0[r]);
; }
; __device__ __forceinline__ void finishSM(f32x16& p0, f32x16& p1, float alpha, float& l_reg, bf16x8& pa0, bf16x8& pa1, bf16x8& pa2, bf16x8& pa3) {
;   for (int r = 0; r < 16; ++r) p1[r] = __builtin_amdgcn_exp2f(p1[r]);
;   float ps = 0; for (int r = 0; r < 16; ++r) ps += p0[r]; for (int r = 0; r < 16; ++r) ps += p1[r];
;   { auto rr = __builtin_amdgcn_permlane32_swap(__float_as_uint(ps), __float_as_uint(ps), false, false);
;     ps = __uint_as_float(rr[0]) + __uint_as_float(rr[1]); }
;   l_reg = l_reg * alpha + ps;
; template <typename TQ>
; __device__ __forceinline__ void attn_dense_body(const TQ* __restrict__ Qb, const bf16* __restrict__ Kh, const bf16* __restrict__ Vh,
;                                                 unsigned short* __restrict__ Ob, int seq, char* lds, const int wave_s) {
;     ...
;     __syncthreads(); SWAIT(); SWRITE(1, SO);
;     RESC(alA); __syncthreads();
.LBB0_585:
	v_xor_b32_e32 v184, 0x8000, v184
	v_xor_b32_e32 v187, 0x8000, v187
	v_xor_b32_e32 v185, 0x18000, v185
	v_mul_f32_e32 v144, 0xbe0293ee, v164
	v_mov_b32_e32 v145, v144
	v_fmamk_f32 v80, v80, 0x3e0293ee, v144
	v_fmamk_f32 v81, v81, 0x3e0293ee, v144
	v_fmamk_f32 v82, v82, 0x3e0293ee, v144
	v_fmamk_f32 v83, v83, 0x3e0293ee, v144
	v_fmamk_f32 v84, v84, 0x3e0293ee, v144
	v_fmamk_f32 v85, v85, 0x3e0293ee, v144
	v_fmamk_f32 v86, v86, 0x3e0293ee, v144
	v_fmamk_f32 v87, v87, 0x3e0293ee, v144
	v_fmamk_f32 v88, v88, 0x3e0293ee, v144
	v_fmamk_f32 v89, v89, 0x3e0293ee, v144
	v_fmamk_f32 v90, v90, 0x3e0293ee, v144
	v_fmamk_f32 v91, v91, 0x3e0293ee, v144
	v_fmamk_f32 v92, v92, 0x3e0293ee, v144
	v_fmamk_f32 v93, v93, 0x3e0293ee, v144
	v_fmamk_f32 v94, v94, 0x3e0293ee, v144
	v_fmac_f32_e32 v145, 0x3e0293ee, v95
	v_exp_f32_e32 v161, v80
	v_exp_f32_e32 v175, v81
	v_exp_f32_e32 v162, v82
	v_exp_f32_e32 v206, v83
	v_exp_f32_e32 v174, v84
	v_exp_f32_e32 v209, v85
	v_exp_f32_e32 v163, v86
	v_exp_f32_e32 v173, v87
	v_exp_f32_e32 v169, v88
	v_exp_f32_e32 v171, v89
	v_exp_f32_e32 v170, v90
	v_exp_f32_e32 v172, v91
	v_exp_f32_e32 v165, v92
	v_exp_f32_e32 v167, v93
	v_exp_f32_e32 v166, v94
	v_exp_f32_e32 v168, v145
	v_pk_fma_f32 v[158:159], v[64:65], s[30:31], v[144:145] op_sel_hi:[1,0,0]
	v_fma_f32 v64, v202, v182, v203
	v_pk_fma_f32 v[156:157], v[66:67], s[30:31], v[144:145] op_sel_hi:[1,0,0]
	v_pk_fma_f32 v[152:153], v[68:69], s[30:31], v[144:145] op_sel_hi:[1,0,0]
	v_pk_fma_f32 v[148:149], v[70:71], s[30:31], v[144:145] op_sel_hi:[1,0,0]
	v_pk_fma_f32 v[146:147], v[72:73], s[30:31], v[144:145] op_sel_hi:[1,0,0]
	v_pk_fma_f32 v[154:155], v[74:75], s[30:31], v[144:145] op_sel_hi:[1,0,0]
	v_pk_fma_f32 v[150:151], v[76:77], s[30:31], v[144:145] op_sel_hi:[1,0,0]
	v_pk_fma_f32 v[144:145], v[78:79], s[30:31], v[144:145] op_sel_hi:[1,0,0]
	v_fma_f32 v182, v64, v205, v207
	s_and_b64 vcc, exec, s[44:45]
	v_mov_b32_e32 v202, v160
	s_waitcnt lgkmcnt(0)
	s_cbranch_vccnz .Lattn_exit
	s_branch .Lattn_head

; #define SBAR() __builtin_amdgcn_sched_barrier(0)
; #define RESC(a) do { if (__any((a) < 1.f)) { if (hi == 0) al_l[r32] = (a); asm volatile("s_waitcnt lgkmcnt(0)" ::: "memory"); \
;     for (int d = 0; d < 4; ++d) for (int r = 0; r < 16; ++r) o[d][r] *= al_l[crow(r, hi)]; } } while (0)
; __device__ __forceinline__ void finishSM(f32x16& p0, f32x16& p1, float alpha, float& l_reg, bf16x8& pa0, bf16x8& pa1, bf16x8& pa2, bf16x8& pa3) {
;     ...
;   { auto rr = __builtin_amdgcn_permlane32_swap(__float_as_uint(ps), __float_as_uint(ps), false, false);
;     ps = __uint_as_float(rr[0]) + __uint_as_float(rr[1]); }
;   l_reg = l_reg * alpha + ps;
; template <typename TQ>
; __device__ __forceinline__ void attn_dense_body(const TQ* __restrict__ Qb, const bf16* __restrict__ Kh, const bf16* __restrict__ Vh,
;                                                 unsigned short* __restrict__ Ob, int seq, char* lds, const int wave_s) {
;     ...
;   SBAR(); qkt(pB0, pB1, (bf16*)((char*)K_lds + SHM_K), qr, r32, hi);
;   finishSM(pA0, pA1, alA, l_reg, pa0, pa1, pa2, pa3); SBAR();
;   pv_d0(o, vb0, pa0, pa1, pa2, pa3); partialSM(pB0, pB1, m_reg, mnB, alB);
;   __syncthreads(); RESC(alB);
.Lattn_exit:
	v_mov_b32_e32 v204, v182
	s_nop 1
	v_permlane32_swap_b32_e32 v182, v204
	v_add_f32_e32 v182, v182, v204
	s_barrier
